# scan: work items remapped so all heads of a batch run on one XCD (shared q/k/kd and B/C hit the same L2); DSA unit end no longer drains its output stores
# speedup vs baseline: 1.2174x; 1.0006x over previous
.LBB0_531:
	s_cmp_lt_i32 s62, 6
	s_cselect_b64 s[6:7], -1, 0
	s_cmp_gt_i32 s61, 5
	s_cselect_b64 s[8:9], -1, 0
	s_and_b64 s[6:7], s[6:7], s[8:9]
	s_andn2_b64 vcc, exec, s[6:7]
	s_cbranch_vccnz .LBB0_742
	s_cmpk_gt_i32 s2, 0xff
	s_cbranch_scc1 .LBB0_688
	v_lshlrev_b32_e32 v1, 3, v192
	v_add_u32_e32 v2, 0x200, v192
	v_and_b32_e32 v0, 0x78, v1
	v_lshrrev_b32_e32 v118, 4, v2
	v_and_b32_e32 v2, 56, v1
	v_sub_u32_e32 v1, 0x11ff, v192
	v_lshrrev_b32_e32 v104, 9, v1
	s_bitcmp0_b32 s63, 0
	v_lshlrev_b32_e32 v4, 2, v192
	v_add_u32_e32 v1, 2, v104
	s_mov_b32 s17, 0
	s_cselect_b64 s[24:25], -1, 0
	s_bitcmp1_b32 s63, 3
	v_and_b32_e32 v120, 30, v1
	v_add_u32_e32 v1, 0, v4
	s_mov_b32 s15, 1
	s_cselect_b64 s[26:27], -1, 0
	v_and_b32_e32 v116, 63, v192
	v_mov_b32_e32 v21, 0
	v_lshrrev_b32_e32 v117, 4, v192
	v_lshrrev_b32_e32 v119, 3, v192
	v_cmp_gt_u32_e64 s[6:7], 32, v192
	v_mov_b32_e32 v105, v104
	v_add_u32_e32 v121, 0x11c00, v1
	s_mov_b32 s14, s17
	s_movk_i32 s3, 0x2c00
	v_lshlrev_b32_e32 v122, 2, v4
	s_movk_i32 s52, 0x2000
	s_movk_i32 s53, 0x110
	s_movk_i32 s54, 0x90
	s_mov_b32 s55, 0x41a00000
	s_mov_b32 s56, 0x800000
	s_mov_b32 s57, 0x3f317217
	s_mov_b32 s58, 0x7f800000
	s_add_i32 s59, 0, 0x1c000
	s_add_i32 s64, 0, 0x15c00
	s_movk_i32 s65, 0x17f
	s_add_i32 s66, 0, 0xcc00
	s_add_i32 s67, 0, 0x11400
	v_lshlrev_b32_e32 v106, 1, v0
	v_lshlrev_b32_e32 v108, 1, v2
	v_mov_b32_e32 v123, 0x41b17218
	v_mov_b32_e32 v124, 0x3fb8aa3b
	s_mov_b32 s68, s2
	s_cmpk_lg_i32 s22, 0x100
	s_cbranch_scc1 .Lscan_noremap
	s_and_b32 s96, s2, 7
	s_lshl_b32 s96, s96, 4
	s_bfe_u32 s97, s2, 0x40003
	s_and_b32 s68, s2, 0x80
	s_or_b32 s68, s68, s96
	s_or_b32 s68, s68, s97
.Lscan_noremap:
	s_branch .LBB0_535
.LBB0_534:
	s_add_i32 s68, s68, s22
	s_cmpk_lt_i32 s68, 0x100
	s_waitcnt lgkmcnt(0)
	s_barrier
	s_cbranch_scc0 .LBB0_688

.LBB0_1625:
	v_add_f32_dpp v0, v157, v157 quad_perm:[1,0,3,2] row_mask:0xf bank_mask:0xf bound_ctrl:1
	s_nop 1
	v_add_f32_dpp v0, v0, v0 quad_perm:[2,3,0,1] row_mask:0xf bank_mask:0xf bound_ctrl:1
	s_nop 1
	v_add_f32_dpp v0, v0, v0 row_half_mirror row_mask:0xf bank_mask:0xf bound_ctrl:1
	s_nop 1
	v_add_f32_dpp v0, v0, v0 row_mirror row_mask:0xf bank_mask:0xf bound_ctrl:1
	v_div_scale_f32 v2, s[6:7], v0, v0, 1.0
	v_rcp_f32_e32 v3, v2
	s_waitcnt vmcnt(0)
	v_div_scale_f32 v4, vcc, 1.0, v0, 1.0
	v_fma_f32 v5, -v2, v3, 1.0
	v_fmac_f32_e32 v3, v5, v3
	v_mul_f32_e32 v5, v4, v3
	v_fma_f32 v6, -v2, v5, v4
	v_fmac_f32_e32 v5, v6, v3
	v_fma_f32 v2, -v2, v5, v4
	v_div_fmas_f32 v2, v2, v3, v5
	v_div_fixup_f32 v0, v2, v0, 1.0
	v_mul_f32_e32 v4, v60, v0
	v_lshl_add_u64 v[2:3], v[176:177], 0, s[10:11]
	v_cvt_pk_bf16_f32 v4, v4, s0
	global_store_short v[2:3], v4, off
	v_mul_f32_e32 v4, v56, v0
	v_cvt_pk_bf16_f32 v4, v4, s0
	global_store_short v[2:3], v4, off offset:32
	v_mul_f32_e32 v4, v52, v0
	v_cvt_pk_bf16_f32 v4, v4, s0
	global_store_short v[2:3], v4, off offset:64
	v_mul_f32_e32 v4, v48, v0
	v_cvt_pk_bf16_f32 v4, v4, s0
	global_store_short v[2:3], v4, off offset:96
	v_mul_f32_e32 v4, v44, v0
	v_cvt_pk_bf16_f32 v4, v4, s0
	global_store_short v[2:3], v4, off offset:128
	v_mul_f32_e32 v4, v40, v0
	v_cvt_pk_bf16_f32 v4, v4, s0
	global_store_short v[2:3], v4, off offset:160
	v_mul_f32_e32 v4, v36, v0
	v_cvt_pk_bf16_f32 v4, v4, s0
	global_store_short v[2:3], v4, off offset:192
	v_mul_f32_e32 v0, v32, v0
	v_add_f32_dpp v4, v156, v156 quad_perm:[1,0,3,2] row_mask:0xf bank_mask:0xf bound_ctrl:1
	v_cvt_pk_bf16_f32 v0, v0, s0
	global_store_short v[2:3], v0, off offset:224
	v_add_f32_dpp v4, v4, v4 quad_perm:[2,3,0,1] row_mask:0xf bank_mask:0xf bound_ctrl:1
	s_nop 1
	v_add_f32_dpp v4, v4, v4 row_half_mirror row_mask:0xf bank_mask:0xf bound_ctrl:1
	s_nop 1
	v_add_f32_dpp v4, v4, v4 row_mirror row_mask:0xf bank_mask:0xf bound_ctrl:1
	v_div_scale_f32 v5, s[6:7], v4, v4, 1.0
	v_rcp_f32_e32 v6, v5
	s_nop 0
	v_fma_f32 v0, -v5, v6, 1.0
	v_fmac_f32_e32 v6, v0, v6
	v_div_scale_f32 v0, vcc, 1.0, v4, 1.0
	v_mul_f32_e32 v7, v0, v6
	v_fma_f32 v8, -v5, v7, v0
	v_fmac_f32_e32 v7, v8, v6
	v_fma_f32 v0, -v5, v7, v0
	v_div_fmas_f32 v0, v0, v6, v7
	v_div_fixup_f32 v0, v0, v4, 1.0
	v_mul_f32_e32 v4, v61, v0
	v_cvt_pk_bf16_f32 v4, v4, s0
	global_store_short v[2:3], v4, off offset:256
	v_mul_f32_e32 v4, v57, v0
	v_cvt_pk_bf16_f32 v4, v4, s0
	global_store_short v[2:3], v4, off offset:288
	v_mul_f32_e32 v4, v53, v0
	v_cvt_pk_bf16_f32 v4, v4, s0
	global_store_short v[2:3], v4, off offset:320
	v_mul_f32_e32 v4, v49, v0
	v_cvt_pk_bf16_f32 v4, v4, s0
	global_store_short v[2:3], v4, off offset:352
	v_mul_f32_e32 v4, v45, v0
	v_cvt_pk_bf16_f32 v4, v4, s0
	global_store_short v[2:3], v4, off offset:384
	v_mul_f32_e32 v4, v41, v0
	v_cvt_pk_bf16_f32 v4, v4, s0
	global_store_short v[2:3], v4, off offset:416
	v_mul_f32_e32 v4, v37, v0
	v_cvt_pk_bf16_f32 v4, v4, s0
	global_store_short v[2:3], v4, off offset:448
	v_mul_f32_e32 v0, v33, v0
	v_add_f32_dpp v4, v155, v155 quad_perm:[1,0,3,2] row_mask:0xf bank_mask:0xf bound_ctrl:1
	v_cvt_pk_bf16_f32 v0, v0, s0
	global_store_short v[2:3], v0, off offset:480
	v_add_f32_dpp v4, v4, v4 quad_perm:[2,3,0,1] row_mask:0xf bank_mask:0xf bound_ctrl:1
	s_nop 1
	v_add_f32_dpp v4, v4, v4 row_half_mirror row_mask:0xf bank_mask:0xf bound_ctrl:1
	s_nop 1
	v_add_f32_dpp v4, v4, v4 row_mirror row_mask:0xf bank_mask:0xf bound_ctrl:1
	v_div_scale_f32 v5, s[6:7], v4, v4, 1.0
	v_rcp_f32_e32 v6, v5
	s_nop 0
	v_fma_f32 v0, -v5, v6, 1.0
	v_fmac_f32_e32 v6, v0, v6
	v_div_scale_f32 v0, vcc, 1.0, v4, 1.0
	v_mul_f32_e32 v7, v0, v6
	v_fma_f32 v8, -v5, v7, v0
	v_fmac_f32_e32 v7, v8, v6
	v_fma_f32 v0, -v5, v7, v0
	v_div_fmas_f32 v0, v0, v6, v7
	v_div_fixup_f32 v0, v0, v4, 1.0
	v_mul_f32_e32 v4, v62, v0
	v_cvt_pk_bf16_f32 v4, v4, s0
	global_store_short v[2:3], v4, off offset:512
	v_mul_f32_e32 v4, v58, v0
	v_cvt_pk_bf16_f32 v4, v4, s0
	global_store_short v[2:3], v4, off offset:544
	v_mul_f32_e32 v4, v54, v0
	v_cvt_pk_bf16_f32 v4, v4, s0
	global_store_short v[2:3], v4, off offset:576
	v_mul_f32_e32 v4, v50, v0
	v_cvt_pk_bf16_f32 v4, v4, s0
	global_store_short v[2:3], v4, off offset:608
	v_mul_f32_e32 v4, v46, v0
	v_cvt_pk_bf16_f32 v4, v4, s0
	global_store_short v[2:3], v4, off offset:640
	v_mul_f32_e32 v4, v42, v0
	v_cvt_pk_bf16_f32 v4, v4, s0
	global_store_short v[2:3], v4, off offset:672
	v_mul_f32_e32 v4, v38, v0
	v_cvt_pk_bf16_f32 v4, v4, s0
	global_store_short v[2:3], v4, off offset:704
	v_mul_f32_e32 v0, v34, v0
	v_add_f32_dpp v4, v154, v154 quad_perm:[1,0,3,2] row_mask:0xf bank_mask:0xf bound_ctrl:1
	v_cvt_pk_bf16_f32 v0, v0, s0
	global_store_short v[2:3], v0, off offset:736
	v_add_f32_dpp v4, v4, v4 quad_perm:[2,3,0,1] row_mask:0xf bank_mask:0xf bound_ctrl:1
	s_nop 1
	v_add_f32_dpp v4, v4, v4 row_half_mirror row_mask:0xf bank_mask:0xf bound_ctrl:1
	s_nop 1
	v_add_f32_dpp v4, v4, v4 row_mirror row_mask:0xf bank_mask:0xf bound_ctrl:1
	v_div_scale_f32 v5, s[6:7], v4, v4, 1.0
	v_rcp_f32_e32 v6, v5
	s_nop 0
	v_fma_f32 v0, -v5, v6, 1.0
	v_fmac_f32_e32 v6, v0, v6
	v_div_scale_f32 v0, vcc, 1.0, v4, 1.0
	v_mul_f32_e32 v7, v0, v6
	v_fma_f32 v8, -v5, v7, v0
	v_fmac_f32_e32 v7, v8, v6
	v_fma_f32 v0, -v5, v7, v0
	v_div_fmas_f32 v0, v0, v6, v7
	v_div_fixup_f32 v0, v0, v4, 1.0
	v_mul_f32_e32 v4, v63, v0
	v_cvt_pk_bf16_f32 v4, v4, s0
	global_store_short v[2:3], v4, off offset:768
	v_mul_f32_e32 v4, v59, v0
	v_cvt_pk_bf16_f32 v4, v4, s0
	global_store_short v[2:3], v4, off offset:800
	v_mul_f32_e32 v4, v55, v0
	v_cvt_pk_bf16_f32 v4, v4, s0
	global_store_short v[2:3], v4, off offset:832
	v_mul_f32_e32 v4, v51, v0
	v_cvt_pk_bf16_f32 v4, v4, s0
	global_store_short v[2:3], v4, off offset:864
	v_mul_f32_e32 v4, v47, v0
	v_cvt_pk_bf16_f32 v4, v4, s0
	global_store_short v[2:3], v4, off offset:896
	v_mul_f32_e32 v4, v43, v0
	v_cvt_pk_bf16_f32 v4, v4, s0
	global_store_short v[2:3], v4, off offset:928
	v_mul_f32_e32 v4, v39, v0
	v_mul_f32_e32 v0, v35, v0
	v_cvt_pk_bf16_f32 v4, v4, s0
	v_cvt_pk_bf16_f32 v0, v0, s0
	global_store_short v[2:3], v4, off offset:960
	global_store_short v[2:3], v0, off offset:992
	s_waitcnt lgkmcnt(0)
	s_branch .Lunit_bar
.LBB0_1626:
	s_waitcnt vmcnt(0)
	s_waitcnt vmcnt(0) lgkmcnt(0)
.Lunit_bar:
	s_barrier
.LBB0_1627:
	s_add_i32 s49, s49, s50
	s_andn2_b64 vcc, exec, s[38:39]
	s_mov_b32 s55, s56
	v_mov_b32_e32 v224, v223
	s_waitcnt lgkmcnt(0)
	s_cbranch_vccz .LBB0_2630
